# adds: accumulator zeroing between tiles with 64 v_mov_b64 instead of 127 v_mov_b32 in all five GEMM phases
# speedup vs baseline: 1.0017x; 1.0017x over previous
; template <class Epi, class Sched>
; __device__ __forceinline__ void gemm_phase(LAS unsigned char* lds, const Gemm g, const Sched& S, const Epi& E) {
;     ...
;         const bool has_next = S.next(ui + 1, nxt);
;         const char* nA = has_next ? (const char*)g.A + (size_t)nxt.pm * tstepA + (size_t)nxt.pn * apn : cA; const char* nB = has_next ? (const char*)g.Bt + (size_t)nxt.pn * tstepB : cB;
;     ...
; #pragma unroll
;         for (int a = 0; a < 2; ++a)
; #pragma unroll
;             for (int b = 0; b < 2; ++b)
; #pragma unroll
;                 for (int m = 0; m < 4; ++m)
; #pragma unroll
;                     for (int n = 0; n < 2; ++n) acc[a][b][m][n] = (f32x4){0.f, 0.f, 0.f, 0.f};
;         cur = nxt; cA = nA; cB = nB; ++ui;
.LBB0_95:
	s_ashr_i32 s13, s12, 31
	s_lshl_b64 s[6:7], s[12:13], 19
	s_add_u32 s46, s84, s6
	s_addc_u32 s47, s85, s7
	s_and_b64 s[6:7], s[50:51], exec
	s_cselect_b32 s13, s47, s43
	s_cselect_b32 s57, s46, s42
	s_ashr_i32 s45, s44, 31
	s_lshl_b64 s[6:7], s[44:45], 19
	s_add_u32 s48, s8, s6
	s_addc_u32 s49, s9, s7
	s_and_b64 s[6:7], s[50:51], exec
	s_cselect_b32 s45, s49, s53
	s_cselect_b32 s68, s48, s52
	s_add_u32 s42, s42, 0x40080
	s_addc_u32 s43, s43, 0
	s_add_u32 s52, s52, 0x100
	v_mov_b32_e32 v4, 0
	s_addc_u32 s53, s53, 0
	s_mov_b32 s69, -2
	v_mov_b32_e32 v5, 0
	v_mov_b64_e32 v[6:7], 0
	v_mov_b64_e32 v[8:9], 0
	v_mov_b64_e32 v[10:11], 0
	v_mov_b64_e32 v[12:13], 0
	v_mov_b64_e32 v[14:15], 0
	v_mov_b64_e32 v[16:17], 0
	v_mov_b64_e32 v[18:19], 0
	v_mov_b64_e32 v[20:21], 0
	v_mov_b64_e32 v[22:23], 0
	v_mov_b64_e32 v[24:25], 0
	v_mov_b64_e32 v[26:27], 0
	v_mov_b64_e32 v[28:29], 0
	v_mov_b64_e32 v[30:31], 0
	v_mov_b64_e32 v[32:33], 0
	v_mov_b64_e32 v[34:35], 0
	v_mov_b64_e32 v[36:37], 0
	v_mov_b64_e32 v[38:39], 0
	v_mov_b64_e32 v[40:41], 0
	v_mov_b64_e32 v[42:43], 0
	v_mov_b64_e32 v[44:45], 0
	v_mov_b64_e32 v[46:47], 0
	v_mov_b64_e32 v[48:49], 0
	v_mov_b64_e32 v[50:51], 0
	v_mov_b64_e32 v[52:53], 0
	v_mov_b64_e32 v[54:55], 0
	v_mov_b64_e32 v[56:57], 0
	v_mov_b64_e32 v[58:59], 0
	v_mov_b64_e32 v[60:61], 0
	v_mov_b64_e32 v[62:63], 0
	v_mov_b64_e32 v[64:65], 0
	v_mov_b64_e32 v[66:67], 0
	v_mov_b64_e32 v[68:69], 0
	v_mov_b64_e32 v[70:71], 0
	v_mov_b64_e32 v[72:73], 0
	v_mov_b64_e32 v[74:75], 0
	v_mov_b64_e32 v[76:77], 0
	v_mov_b64_e32 v[78:79], 0
	v_mov_b64_e32 v[80:81], 0
	v_mov_b64_e32 v[82:83], 0
	v_mov_b64_e32 v[84:85], 0
	v_mov_b64_e32 v[86:87], 0
	v_mov_b64_e32 v[88:89], 0
	v_mov_b64_e32 v[90:91], 0
	v_mov_b64_e32 v[92:93], 0
	v_mov_b64_e32 v[94:95], 0
	v_mov_b64_e32 v[96:97], 0
	v_mov_b64_e32 v[98:99], 0
	v_mov_b64_e32 v[100:101], 0
	v_mov_b64_e32 v[102:103], 0
	v_mov_b64_e32 v[104:105], 0
	v_mov_b64_e32 v[106:107], 0
	v_mov_b64_e32 v[108:109], 0
	v_mov_b64_e32 v[110:111], 0
	v_mov_b64_e32 v[112:113], 0
	v_mov_b64_e32 v[114:115], 0
	v_mov_b64_e32 v[116:117], 0
	v_mov_b64_e32 v[118:119], 0
	v_mov_b64_e32 v[120:121], 0
	v_mov_b64_e32 v[122:123], 0
	v_mov_b64_e32 v[124:125], 0
	v_mov_b64_e32 v[126:127], 0
	v_mov_b64_e32 v[128:129], 0
	v_mov_b64_e32 v[130:131], 0

; template <class Epi, class Sched>
; __device__ __forceinline__ void gemm_phase(LAS unsigned char* lds, const Gemm g, const Sched& S, const Epi& E) {
;     ...
; #pragma unroll
;         for (int a = 0; a < 2; ++a)
; #pragma unroll
;             for (int b = 0; b < 2; ++b)
; #pragma unroll
;                 for (int m = 0; m < 4; ++m)
; #pragma unroll
;                     for (int n = 0; n < 2; ++n) acc[a][b][m][n] = (f32x4){0.f, 0.f, 0.f, 0.f};
;         cur = nxt; cA = nA; cB = nB; ++ui;
.LBB0_357:
	s_ashr_i32 s43, s42, 31
	s_lshl_b64 s[6:7], s[42:43], 19
	v_readlane_b32 s14, v253, 21
	v_readlane_b32 s15, v253, 22
	s_add_u32 s46, s14, s6
	s_addc_u32 s47, s15, s7
	s_and_b64 s[6:7], s[44:45], exec
	s_cselect_b32 s9, s47, s53
	s_cselect_b32 s13, s46, s52
	s_ashr_i32 s23, s22, 31
	s_lshl_b64 s[6:7], s[22:23], 19
	s_add_u32 s48, s28, s6
	s_addc_u32 s49, s35, s7
	s_and_b64 s[6:7], s[44:45], exec
	s_cselect_b32 s21, s49, s55
	s_cselect_b32 s23, s48, s54
	s_add_u32 s52, s52, 0x40080
	s_addc_u32 s53, s53, 0
	s_add_u32 s33, s54, 0x100
	v_mov_b32_e32 v0, 0
	s_addc_u32 s43, s55, 0
	s_mov_b32 s54, -2
	s_waitcnt lgkmcnt(0)
	v_mov_b32_e32 v1, 0
	v_mov_b64_e32 v[2:3], 0
	v_mov_b64_e32 v[4:5], 0
	v_mov_b64_e32 v[6:7], 0
	v_mov_b64_e32 v[8:9], 0
	v_mov_b64_e32 v[10:11], 0
	v_mov_b64_e32 v[12:13], 0
	v_mov_b64_e32 v[14:15], 0
	v_mov_b64_e32 v[16:17], 0
	v_mov_b64_e32 v[18:19], 0
	v_mov_b64_e32 v[20:21], 0
	v_mov_b64_e32 v[22:23], 0
	v_mov_b64_e32 v[24:25], 0
	v_mov_b64_e32 v[26:27], 0
	v_mov_b64_e32 v[28:29], 0
	v_mov_b64_e32 v[30:31], 0
	v_mov_b64_e32 v[32:33], 0
	v_mov_b64_e32 v[34:35], 0
	v_mov_b64_e32 v[36:37], 0
	v_mov_b64_e32 v[38:39], 0
	v_mov_b64_e32 v[40:41], 0
	v_mov_b64_e32 v[42:43], 0
	v_mov_b64_e32 v[44:45], 0
	v_mov_b64_e32 v[46:47], 0
	v_mov_b64_e32 v[48:49], 0
	v_mov_b64_e32 v[50:51], 0
	v_mov_b64_e32 v[52:53], 0
	v_mov_b64_e32 v[54:55], 0
	v_mov_b64_e32 v[56:57], 0
	v_mov_b64_e32 v[58:59], 0
	v_mov_b64_e32 v[60:61], 0
	v_mov_b64_e32 v[62:63], 0
	v_mov_b64_e32 v[64:65], 0
	v_mov_b64_e32 v[66:67], 0
	v_mov_b64_e32 v[68:69], 0
	v_mov_b64_e32 v[70:71], 0
	v_mov_b64_e32 v[72:73], 0
	v_mov_b64_e32 v[74:75], 0
	v_mov_b64_e32 v[76:77], 0
	v_mov_b64_e32 v[78:79], 0
	v_mov_b64_e32 v[80:81], 0
	v_mov_b64_e32 v[82:83], 0
	v_mov_b64_e32 v[84:85], 0
	v_mov_b64_e32 v[86:87], 0
	v_mov_b64_e32 v[88:89], 0
	v_mov_b64_e32 v[90:91], 0
	v_mov_b64_e32 v[92:93], 0
	v_mov_b64_e32 v[94:95], 0
	v_mov_b64_e32 v[96:97], 0
	v_mov_b64_e32 v[98:99], 0
	v_mov_b64_e32 v[100:101], 0
	v_mov_b64_e32 v[102:103], 0
	v_mov_b64_e32 v[104:105], 0
	v_mov_b64_e32 v[106:107], 0
	v_mov_b64_e32 v[108:109], 0
	v_mov_b64_e32 v[110:111], 0
	v_mov_b64_e32 v[112:113], 0
	v_mov_b64_e32 v[114:115], 0
	v_mov_b64_e32 v[116:117], 0
	v_mov_b64_e32 v[118:119], 0
	v_mov_b64_e32 v[120:121], 0
	v_mov_b64_e32 v[122:123], 0
	v_mov_b64_e32 v[124:125], 0
	v_mov_b64_e32 v[126:127], 0

; template <class Epi, class Sched>
; __device__ __forceinline__ void gemm_phase(LAS unsigned char* lds, const Gemm g, const Sched& S, const Epi& E) {
;     ...
; #pragma unroll
;         for (int a = 0; a < 2; ++a)
; #pragma unroll
;             for (int b = 0; b < 2; ++b)
; #pragma unroll
;                 for (int m = 0; m < 4; ++m)
; #pragma unroll
;                     for (int n = 0; n < 2; ++n) acc[a][b][m][n] = (f32x4){0.f, 0.f, 0.f, 0.f};
;         cur = nxt; cA = nA; cB = nB; ++ui;
.LBB0_627:
	s_lshl_b64 s[6:7], s[22:23], 17
	s_add_u32 s46, s28, s6
	s_addc_u32 s47, s20, s7
	s_and_b64 s[6:7], exec, s[42:43]
	v_mov_b32_e32 v0, 0
	s_cselect_b32 s9, s47, s51
	s_cselect_b32 s13, s46, s50
	s_mov_b32 s6, 0
	s_mov_b64 s[54:55], -1
	s_mov_b64 s[56:57], 0
	s_waitcnt lgkmcnt(0)
	v_mov_b32_e32 v1, 0
	v_mov_b64_e32 v[2:3], 0
	v_mov_b64_e32 v[4:5], 0
	v_mov_b64_e32 v[6:7], 0
	v_mov_b64_e32 v[8:9], 0
	v_mov_b64_e32 v[10:11], 0
	v_mov_b64_e32 v[12:13], 0
	v_mov_b64_e32 v[14:15], 0
	v_mov_b64_e32 v[16:17], 0
	v_mov_b64_e32 v[18:19], 0
	v_mov_b64_e32 v[20:21], 0
	v_mov_b64_e32 v[22:23], 0
	v_mov_b64_e32 v[24:25], 0
	v_mov_b64_e32 v[26:27], 0
	v_mov_b64_e32 v[28:29], 0
	v_mov_b64_e32 v[30:31], 0
	v_mov_b64_e32 v[32:33], 0
	v_mov_b64_e32 v[34:35], 0
	v_mov_b64_e32 v[36:37], 0
	v_mov_b64_e32 v[38:39], 0
	v_mov_b64_e32 v[40:41], 0
	v_mov_b64_e32 v[42:43], 0
	v_mov_b64_e32 v[44:45], 0
	v_mov_b64_e32 v[46:47], 0
	v_mov_b64_e32 v[48:49], 0
	v_mov_b64_e32 v[50:51], 0
	v_mov_b64_e32 v[52:53], 0
	v_mov_b64_e32 v[54:55], 0
	v_mov_b64_e32 v[56:57], 0
	v_mov_b64_e32 v[58:59], 0
	v_mov_b64_e32 v[60:61], 0
	v_mov_b64_e32 v[62:63], 0
	v_mov_b64_e32 v[64:65], 0
	v_mov_b64_e32 v[66:67], 0
	v_mov_b64_e32 v[68:69], 0
	v_mov_b64_e32 v[70:71], 0
	v_mov_b64_e32 v[72:73], 0
	v_mov_b64_e32 v[74:75], 0
	v_mov_b64_e32 v[76:77], 0
	v_mov_b64_e32 v[78:79], 0
	v_mov_b64_e32 v[80:81], 0
	v_mov_b64_e32 v[82:83], 0
	v_mov_b64_e32 v[84:85], 0
	v_mov_b64_e32 v[86:87], 0
	v_mov_b64_e32 v[88:89], 0
	v_mov_b64_e32 v[90:91], 0
	v_mov_b64_e32 v[92:93], 0
	v_mov_b64_e32 v[94:95], 0
	v_mov_b64_e32 v[96:97], 0
	v_mov_b64_e32 v[98:99], 0
	v_mov_b64_e32 v[100:101], 0
	v_mov_b64_e32 v[102:103], 0
	v_mov_b64_e32 v[104:105], 0
	v_mov_b64_e32 v[106:107], 0
	v_mov_b64_e32 v[108:109], 0
	v_mov_b64_e32 v[110:111], 0
	v_mov_b64_e32 v[112:113], 0
	v_mov_b64_e32 v[114:115], 0
	v_mov_b64_e32 v[116:117], 0
	v_mov_b64_e32 v[118:119], 0
	v_mov_b64_e32 v[120:121], 0
	v_mov_b64_e32 v[122:123], 0
	v_mov_b64_e32 v[124:125], 0
	v_mov_b64_e32 v[126:127], 0

; template <class Epi, class Sched>
; __device__ __forceinline__ void gemm_phase(LAS unsigned char* lds, const Gemm g, const Sched& S, const Epi& E) {
;     ...
;         const bool has_next = S.next(ui + 1, nxt);
;         const char* nA = has_next ? (const char*)g.A + (size_t)nxt.pm * tstepA + (size_t)nxt.pn * apn : cA; const char* nB = has_next ? (const char*)g.Bt + (size_t)nxt.pn * tstepB : cB;
;     ...
; #pragma unroll
;         for (int a = 0; a < 2; ++a)
; #pragma unroll
;             for (int b = 0; b < 2; ++b)
; #pragma unroll
;                 for (int m = 0; m < 4; ++m)
; #pragma unroll
;                     for (int n = 0; n < 2; ++n) acc[a][b][m][n] = (f32x4){0.f, 0.f, 0.f, 0.f};
;         cur = nxt; cA = nA; cB = nB; ++ui;
.LBB0_717:
	s_ashr_i32 s23, s22, 31
	s_lshl_b64 s[14:15], s[22:23], 19
	s_add_u32 s34, s84, s14
	s_addc_u32 s35, s85, s15
	s_and_b64 s[14:15], s[42:43], exec
	s_cselect_b32 s23, s35, s7
	s_cselect_b32 s53, s34, s6
	s_ashr_i32 s19, s18, 31
	s_lshl_b64 s[14:15], s[18:19], 19
	s_add_u32 s40, s28, s14
	s_addc_u32 s41, s48, s15
	s_and_b64 s[14:15], s[42:43], exec
	s_cselect_b32 s19, s41, s47
	s_cselect_b32 s54, s40, s46
	s_add_u32 s44, s6, 0x40080
	s_addc_u32 s45, s7, 0
	s_add_u32 s46, s46, 0x100
	v_mov_b32_e32 v4, 0
	s_addc_u32 s47, s47, 0
	s_mov_b32 s55, -2
	v_mov_b32_e32 v5, 0
	v_mov_b64_e32 v[6:7], 0
	v_mov_b64_e32 v[8:9], 0
	v_mov_b64_e32 v[10:11], 0
	v_mov_b64_e32 v[12:13], 0
	v_mov_b64_e32 v[14:15], 0
	v_mov_b64_e32 v[16:17], 0
	v_mov_b64_e32 v[18:19], 0
	v_mov_b64_e32 v[20:21], 0
	v_mov_b64_e32 v[22:23], 0
	v_mov_b64_e32 v[24:25], 0
	v_mov_b64_e32 v[26:27], 0
	v_mov_b64_e32 v[28:29], 0
	v_mov_b64_e32 v[30:31], 0
	v_mov_b64_e32 v[32:33], 0
	v_mov_b64_e32 v[34:35], 0
	v_mov_b64_e32 v[36:37], 0
	v_mov_b64_e32 v[38:39], 0
	v_mov_b64_e32 v[40:41], 0
	v_mov_b64_e32 v[42:43], 0
	v_mov_b64_e32 v[44:45], 0
	v_mov_b64_e32 v[46:47], 0
	v_mov_b64_e32 v[48:49], 0
	v_mov_b64_e32 v[50:51], 0
	v_mov_b64_e32 v[52:53], 0
	v_mov_b64_e32 v[54:55], 0
	v_mov_b64_e32 v[56:57], 0
	v_mov_b64_e32 v[58:59], 0
	v_mov_b64_e32 v[60:61], 0
	v_mov_b64_e32 v[62:63], 0
	v_mov_b64_e32 v[64:65], 0
	v_mov_b64_e32 v[66:67], 0
	v_mov_b64_e32 v[68:69], 0
	v_mov_b64_e32 v[70:71], 0
	v_mov_b64_e32 v[72:73], 0
	v_mov_b64_e32 v[74:75], 0
	v_mov_b64_e32 v[76:77], 0
	v_mov_b64_e32 v[78:79], 0
	v_mov_b64_e32 v[80:81], 0
	v_mov_b64_e32 v[82:83], 0
	v_mov_b64_e32 v[84:85], 0
	v_mov_b64_e32 v[86:87], 0
	v_mov_b64_e32 v[88:89], 0
	v_mov_b64_e32 v[90:91], 0
	v_mov_b64_e32 v[92:93], 0
	v_mov_b64_e32 v[94:95], 0
	v_mov_b64_e32 v[96:97], 0
	v_mov_b64_e32 v[98:99], 0
	v_mov_b64_e32 v[100:101], 0
	v_mov_b64_e32 v[102:103], 0
	v_mov_b64_e32 v[104:105], 0
	v_mov_b64_e32 v[106:107], 0
	v_mov_b64_e32 v[108:109], 0
	v_mov_b64_e32 v[110:111], 0
	v_mov_b64_e32 v[112:113], 0
	v_mov_b64_e32 v[114:115], 0
	v_mov_b64_e32 v[116:117], 0
	v_mov_b64_e32 v[118:119], 0
	v_mov_b64_e32 v[120:121], 0
	v_mov_b64_e32 v[122:123], 0
	v_mov_b64_e32 v[124:125], 0
	v_mov_b64_e32 v[126:127], 0
	v_mov_b64_e32 v[128:129], 0
	v_mov_b64_e32 v[130:131], 0

; template <class Epi, class Sched>
; __device__ __forceinline__ void gemm_phase(LAS unsigned char* lds, const Gemm g, const Sched& S, const Epi& E) {
;     ...
; #pragma unroll
;         for (int a = 0; a < 2; ++a)
; #pragma unroll
;             for (int b = 0; b < 2; ++b)
; #pragma unroll
;                 for (int m = 0; m < 4; ++m)
; #pragma unroll
;                     for (int n = 0; n < 2; ++n) acc[a][b][m][n] = (f32x4){0.f, 0.f, 0.f, 0.f};
;         cur = nxt; cA = nA; cB = nB; ++ui;
.LBB0_806:
	s_add_u32 s33, s46, 0x100
	v_mov_b32_e32 v0, 0
	s_addc_u32 s53, s47, 0
	s_mov_b32 s54, -2
	s_waitcnt lgkmcnt(0)
	v_mov_b32_e32 v1, 0
	v_mov_b64_e32 v[2:3], 0
	v_mov_b64_e32 v[4:5], 0
	v_mov_b64_e32 v[6:7], 0
	v_mov_b64_e32 v[8:9], 0
	v_mov_b64_e32 v[10:11], 0
	v_mov_b64_e32 v[12:13], 0
	v_mov_b64_e32 v[14:15], 0
	v_mov_b64_e32 v[16:17], 0
	v_mov_b64_e32 v[18:19], 0
	v_mov_b64_e32 v[20:21], 0
	v_mov_b64_e32 v[22:23], 0
	v_mov_b64_e32 v[24:25], 0
	v_mov_b64_e32 v[26:27], 0
	v_mov_b64_e32 v[28:29], 0
	v_mov_b64_e32 v[30:31], 0
	v_mov_b64_e32 v[32:33], 0
	v_mov_b64_e32 v[34:35], 0
	v_mov_b64_e32 v[36:37], 0
	v_mov_b64_e32 v[38:39], 0
	v_mov_b64_e32 v[40:41], 0
	v_mov_b64_e32 v[42:43], 0
	v_mov_b64_e32 v[44:45], 0
	v_mov_b64_e32 v[46:47], 0
	v_mov_b64_e32 v[48:49], 0
	v_mov_b64_e32 v[50:51], 0
	v_mov_b64_e32 v[52:53], 0
	v_mov_b64_e32 v[54:55], 0
	v_mov_b64_e32 v[56:57], 0
	v_mov_b64_e32 v[58:59], 0
	v_mov_b64_e32 v[60:61], 0
	v_mov_b64_e32 v[62:63], 0
	v_mov_b64_e32 v[64:65], 0
	v_mov_b64_e32 v[66:67], 0
	v_mov_b64_e32 v[68:69], 0
	v_mov_b64_e32 v[70:71], 0
	v_mov_b64_e32 v[72:73], 0
	v_mov_b64_e32 v[74:75], 0
	v_mov_b64_e32 v[76:77], 0
	v_mov_b64_e32 v[78:79], 0
	v_mov_b64_e32 v[80:81], 0
	v_mov_b64_e32 v[82:83], 0
	v_mov_b64_e32 v[84:85], 0
	v_mov_b64_e32 v[86:87], 0
	v_mov_b64_e32 v[88:89], 0
	v_mov_b64_e32 v[90:91], 0
	v_mov_b64_e32 v[92:93], 0
	v_mov_b64_e32 v[94:95], 0
	v_mov_b64_e32 v[96:97], 0
	v_mov_b64_e32 v[98:99], 0
	v_mov_b64_e32 v[100:101], 0
	v_mov_b64_e32 v[102:103], 0
	v_mov_b64_e32 v[104:105], 0
	v_mov_b64_e32 v[106:107], 0
	v_mov_b64_e32 v[108:109], 0
	v_mov_b64_e32 v[110:111], 0
	v_mov_b64_e32 v[112:113], 0
	v_mov_b64_e32 v[114:115], 0
	v_mov_b64_e32 v[116:117], 0
	v_mov_b64_e32 v[118:119], 0
	v_mov_b64_e32 v[120:121], 0
	v_mov_b64_e32 v[122:123], 0
	v_mov_b64_e32 v[124:125], 0
	v_mov_b64_e32 v[126:127], 0
